# w_out GEMM fused LayerNorm epilogue: first 6 residual load groups issued as one batch into dead fragment registers (on top of the same change in the FFN-down epilogue)
# baseline (speedup 1.0000x reference)
; __device__ __forceinline__ float bf_lo(unsigned w) { return __uint_as_float(w << 16); }
; __device__ __forceinline__ float bf_hi(unsigned w) { return __uint_as_float(w & 0xffff0000u); }
;     __device__ __forceinline__ void operator()(pg8::f32x4 (&acc)[2][2][4][2], const pg8::Unit& u, int wr, int wc, int fr, int fq) const {
;         typedef float f32x2v __attribute__((ext_vector_type(2)));
;         const int wid = wr * 4 + wc, lane = fq * 16 + fr;
;         const size_t off0 = ((size_t)u.pm * 256 + wr * 64 + fr) * DM + (size_t)u.pn * 256 + wc * 32 + 4 * fq;
; #pragma unroll
;         for (int ai = 0; ai < 2; ++ai)
; #pragma unroll
;             for (int m = 0; m < 4; ++m) {
; #pragma unroll
;                 for (int bj = 0; bj < 2; ++bj)
; #pragma unroll
;                     for (int n = 0; n < 2; ++n) { const size_t o_ = off0 + (size_t)(ai * 128 + m * 16) * DM + bj * 128 + n * 16; pg8::f32x4 bs;
;                         if (BASE_BF16) { const v2u w = *(const v2u*)((const bf16*)basev + o_); bs = (pg8::f32x4){pg8::bf_lo(w.x), pg8::bf_hi(w.x), pg8::bf_lo(w.y), pg8::bf_hi(w.y)}; }
;                         else bs = *(const pg8::f32x4*)((const float*)basev + o_);
;                         acc[ai][bj][m][n] = bs * ALPHA + acc[ai][bj][m][n]; }
;                 asm volatile("" : "+v"(acc[ai][0][m][0]), "+v"(acc[ai][0][m][1]), "+v"(acc[ai][1][m][0]), "+v"(acc[ai][1][m][1]));
;                 if (m & 1) asm volatile("" ::: "memory"); }
.LBB0_1601:
	s_ashr_i32 s71, s70, 31
	s_ashr_i32 s13, s12, 31
	s_lshl_b64 s[72:73], s[70:71], 9
	v_lshl_add_u64 v[130:131], v[154:155], 0, s[72:73]
	s_lshl_b64 s[72:73], s[12:13], 19
	v_lshl_add_u64 v[168:169], v[130:131], 0, s[72:73]
	global_load_dwordx2 v[202:203], v[168:169], off
	global_load_dwordx2 v[204:205], v[168:169], off offset:32
	global_load_dwordx2 v[206:207], v[168:169], off offset:256
	global_load_dwordx2 v[208:209], v[168:169], off offset:288
	v_add_co_u32_e32 v138, vcc, 0x8000, v168
	s_nop 1
	v_addc_co_u32_e32 v139, vcc, 0, v169, vcc
	global_load_dwordx2 v[210:211], v[138:139], off
	global_load_dwordx2 v[212:213], v[138:139], off offset:32
	global_load_dwordx2 v[214:215], v[138:139], off offset:256
	global_load_dwordx2 v[216:217], v[138:139], off offset:288
	v_add_co_u32_e32 v138, vcc, 0x10000, v168
	s_nop 1
	v_addc_co_u32_e32 v139, vcc, 0, v169, vcc
	global_load_dwordx2 v[218:219], v[138:139], off
	global_load_dwordx2 v[220:221], v[138:139], off offset:32
	global_load_dwordx2 v[222:223], v[138:139], off offset:256
	global_load_dwordx2 v[224:225], v[138:139], off offset:288
	v_add_co_u32_e32 v138, vcc, 0x18000, v168
	s_nop 1
	v_addc_co_u32_e32 v139, vcc, 0, v169, vcc
	global_load_dwordx2 v[226:227], v[138:139], off
	global_load_dwordx2 v[228:229], v[138:139], off offset:32
	global_load_dwordx2 v[230:231], v[138:139], off offset:256
	global_load_dwordx2 v[232:233], v[138:139], off offset:288
	v_add_co_u32_e32 v138, vcc, 0x40000, v168
	s_nop 1
	v_addc_co_u32_e32 v139, vcc, 0, v169, vcc
	global_load_dwordx2 v[234:235], v[138:139], off
	global_load_dwordx2 v[236:237], v[138:139], off offset:32
	global_load_dwordx2 v[238:239], v[138:139], off offset:256
	global_load_dwordx2 v[240:241], v[138:139], off offset:288
	v_add_co_u32_e32 v138, vcc, 0x48000, v168
	s_nop 1
	v_addc_co_u32_e32 v139, vcc, 0, v169, vcc
	global_load_dwordx2 v[242:243], v[138:139], off
	global_load_dwordx2 v[244:245], v[138:139], off offset:32
	global_load_dwordx2 v[246:247], v[138:139], off offset:256
	global_load_dwordx2 v[248:249], v[138:139], off offset:288
	s_mov_b32 s13, 0x8000
	v_add_co_u32_e32 v138, vcc, s13, v168
	s_mov_b32 s13, 0x10000
	s_nop 0
	v_addc_co_u32_e32 v139, vcc, 0, v169, vcc
	s_waitcnt vmcnt(20)
	v_lshlrev_b32_e32 v140, 16, v202
	v_and_b32_e32 v141, 0xffff0000, v202
	v_lshlrev_b32_e32 v130, 16, v203
	v_and_b32_e32 v131, 0xffff0000, v203
	v_lshlrev_b32_e32 v142, 16, v204
	v_and_b32_e32 v143, 0xffff0000, v204
	v_lshlrev_b32_e32 v132, 16, v205
	v_and_b32_e32 v133, 0xffff0000, v205
	v_lshlrev_b32_e32 v144, 16, v206
	v_and_b32_e32 v145, 0xffff0000, v206
	v_lshlrev_b32_e32 v134, 16, v207
	v_and_b32_e32 v135, 0xffff0000, v207
	v_lshlrev_b32_e32 v146, 16, v208
	v_and_b32_e32 v147, 0xffff0000, v208
	v_lshlrev_b32_e32 v136, 16, v209
	v_and_b32_e32 v137, 0xffff0000, v209
	v_pk_fma_f32 v[28:29], v[130:131], s[40:41], v[28:29] op_sel_hi:[1,0,1]
	v_pk_fma_f32 v[26:27], v[140:141], s[40:41], v[26:27] op_sel_hi:[1,0,1]
	v_pk_fma_f32 v[16:17], v[132:133], s[40:41], v[16:17] op_sel_hi:[1,0,1]
	v_pk_fma_f32 v[14:15], v[142:143], s[40:41], v[14:15] op_sel_hi:[1,0,1]
	v_pk_fma_f32 v[8:9], v[134:135], s[40:41], v[8:9] op_sel_hi:[1,0,1]
	v_pk_fma_f32 v[6:7], v[144:145], s[40:41], v[6:7] op_sel_hi:[1,0,1]
	v_pk_fma_f32 v[4:5], v[136:137], s[40:41], v[4:5] op_sel_hi:[1,0,1]
	v_pk_fma_f32 v[2:3], v[146:147], s[40:41], v[2:3] op_sel_hi:[1,0,1]
	s_nop 0
	v_add_co_u32_e32 v138, vcc, s13, v168
	s_mov_b32 s13, 0x18000
	s_nop 0
	v_addc_co_u32_e32 v139, vcc, 0, v169, vcc
	s_waitcnt vmcnt(19)
	v_lshlrev_b32_e32 v140, 16, v210
	v_and_b32_e32 v141, 0xffff0000, v210
	v_lshlrev_b32_e32 v130, 16, v211
	v_and_b32_e32 v131, 0xffff0000, v211
	s_waitcnt vmcnt(18)
	v_lshlrev_b32_e32 v142, 16, v212
	v_and_b32_e32 v143, 0xffff0000, v212
	v_lshlrev_b32_e32 v132, 16, v213
	v_and_b32_e32 v133, 0xffff0000, v213
	s_waitcnt vmcnt(17)
	v_lshlrev_b32_e32 v144, 16, v214
	v_and_b32_e32 v145, 0xffff0000, v214
	v_lshlrev_b32_e32 v134, 16, v215
	v_and_b32_e32 v135, 0xffff0000, v215
	s_waitcnt vmcnt(16)
	v_lshlrev_b32_e32 v146, 16, v216
	v_and_b32_e32 v147, 0xffff0000, v216
	v_lshlrev_b32_e32 v136, 16, v217
	v_and_b32_e32 v137, 0xffff0000, v217
	v_pk_fma_f32 v[44:45], v[130:131], s[40:41], v[44:45] op_sel_hi:[1,0,1]
	v_pk_fma_f32 v[42:43], v[140:141], s[40:41], v[42:43] op_sel_hi:[1,0,1]
	v_pk_fma_f32 v[32:33], v[132:133], s[40:41], v[32:33] op_sel_hi:[1,0,1]
	v_pk_fma_f32 v[30:31], v[142:143], s[40:41], v[30:31] op_sel_hi:[1,0,1]
	v_pk_fma_f32 v[20:21], v[134:135], s[40:41], v[20:21] op_sel_hi:[1,0,1]
	v_pk_fma_f32 v[18:19], v[144:145], s[40:41], v[18:19] op_sel_hi:[1,0,1]
	v_pk_fma_f32 v[12:13], v[136:137], s[40:41], v[12:13] op_sel_hi:[1,0,1]
	v_pk_fma_f32 v[10:11], v[146:147], s[40:41], v[10:11] op_sel_hi:[1,0,1]
	s_nop 0
	v_add_co_u32_e32 v138, vcc, s13, v168
	s_mov_b32 s13, 0x40000
	s_nop 0
	v_addc_co_u32_e32 v139, vcc, 0, v169, vcc
	s_waitcnt vmcnt(15)
	v_lshlrev_b32_e32 v140, 16, v218
	v_and_b32_e32 v141, 0xffff0000, v218
	v_lshlrev_b32_e32 v130, 16, v219
	v_and_b32_e32 v131, 0xffff0000, v219
	s_waitcnt vmcnt(14)
	v_lshlrev_b32_e32 v142, 16, v220
	v_and_b32_e32 v143, 0xffff0000, v220
	v_lshlrev_b32_e32 v132, 16, v221
	v_and_b32_e32 v133, 0xffff0000, v221
	s_waitcnt vmcnt(13)
	v_lshlrev_b32_e32 v144, 16, v222
	v_and_b32_e32 v145, 0xffff0000, v222
	v_lshlrev_b32_e32 v134, 16, v223
	v_and_b32_e32 v135, 0xffff0000, v223
	s_waitcnt vmcnt(12)
; __device__ __forceinline__ float bf_lo(unsigned w) { return __uint_as_float(w << 16); }
; __device__ __forceinline__ float bf_hi(unsigned w) { return __uint_as_float(w & 0xffff0000u); }
;     __device__ __forceinline__ void operator()(pg8::f32x4 (&acc)[2][2][4][2], const pg8::Unit& u, int wr, int wc, int fr, int fq) const {
;     ...
;         for (int ai = 0; ai < 2; ++ai)
; #pragma unroll
;             for (int m = 0; m < 4; ++m) {
; #pragma unroll
;                 for (int bj = 0; bj < 2; ++bj)
; #pragma unroll
;                     for (int n = 0; n < 2; ++n) { const size_t o_ = off0 + (size_t)(ai * 128 + m * 16) * DM + bj * 128 + n * 16; pg8::f32x4 bs;
;                         if (BASE_BF16) { const v2u w = *(const v2u*)((const bf16*)basev + o_); bs = (pg8::f32x4){pg8::bf_lo(w.x), pg8::bf_hi(w.x), pg8::bf_lo(w.y), pg8::bf_hi(w.y)}; }
;                         else bs = *(const pg8::f32x4*)((const float*)basev + o_);
;                         acc[ai][bj][m][n] = bs * ALPHA + acc[ai][bj][m][n]; }
;                 asm volatile("" : "+v"(acc[ai][0][m][0]), "+v"(acc[ai][0][m][1]), "+v"(acc[ai][1][m][0]), "+v"(acc[ai][1][m][1]));
;                 if (m & 1) asm volatile("" ::: "memory"); }
	v_lshlrev_b32_e32 v146, 16, v224
	v_and_b32_e32 v147, 0xffff0000, v224
	v_lshlrev_b32_e32 v136, 16, v225
	v_and_b32_e32 v137, 0xffff0000, v225
	v_pk_fma_f32 v[76:77], v[130:131], s[40:41], v[76:77] op_sel_hi:[1,0,1]
	v_pk_fma_f32 v[74:75], v[140:141], s[40:41], v[74:75] op_sel_hi:[1,0,1]
	v_pk_fma_f32 v[48:49], v[132:133], s[40:41], v[48:49] op_sel_hi:[1,0,1]
	v_pk_fma_f32 v[46:47], v[142:143], s[40:41], v[46:47] op_sel_hi:[1,0,1]
	v_pk_fma_f32 v[36:37], v[134:135], s[40:41], v[36:37] op_sel_hi:[1,0,1]
	v_pk_fma_f32 v[34:35], v[144:145], s[40:41], v[34:35] op_sel_hi:[1,0,1]
	v_pk_fma_f32 v[24:25], v[136:137], s[40:41], v[24:25] op_sel_hi:[1,0,1]
	v_pk_fma_f32 v[22:23], v[146:147], s[40:41], v[22:23] op_sel_hi:[1,0,1]
	s_nop 0
	v_add_co_u32_e32 v138, vcc, s13, v168
	s_mov_b32 s13, 0x48000
	s_nop 0
	v_addc_co_u32_e32 v139, vcc, 0, v169, vcc
	s_waitcnt vmcnt(11)
	v_lshlrev_b32_e32 v140, 16, v226
	v_and_b32_e32 v141, 0xffff0000, v226
	v_lshlrev_b32_e32 v130, 16, v227
	v_and_b32_e32 v131, 0xffff0000, v227
	s_waitcnt vmcnt(10)
	v_lshlrev_b32_e32 v142, 16, v228
	v_and_b32_e32 v143, 0xffff0000, v228
	v_lshlrev_b32_e32 v132, 16, v229
	v_and_b32_e32 v133, 0xffff0000, v229
	s_waitcnt vmcnt(9)
	v_lshlrev_b32_e32 v144, 16, v230
	v_and_b32_e32 v145, 0xffff0000, v230
	v_lshlrev_b32_e32 v134, 16, v231
	v_and_b32_e32 v135, 0xffff0000, v231
	s_waitcnt vmcnt(8)
	v_lshlrev_b32_e32 v146, 16, v232
	v_and_b32_e32 v147, 0xffff0000, v232
	v_lshlrev_b32_e32 v136, 16, v233
	v_and_b32_e32 v137, 0xffff0000, v233
	v_pk_fma_f32 v[92:93], v[130:131], s[40:41], v[92:93] op_sel_hi:[1,0,1]
	v_pk_fma_f32 v[90:91], v[140:141], s[40:41], v[90:91] op_sel_hi:[1,0,1]
	v_pk_fma_f32 v[80:81], v[132:133], s[40:41], v[80:81] op_sel_hi:[1,0,1]
	v_pk_fma_f32 v[78:79], v[142:143], s[40:41], v[78:79] op_sel_hi:[1,0,1]
	v_pk_fma_f32 v[52:53], v[134:135], s[40:41], v[52:53] op_sel_hi:[1,0,1]
	v_pk_fma_f32 v[50:51], v[144:145], s[40:41], v[50:51] op_sel_hi:[1,0,1]
	v_pk_fma_f32 v[40:41], v[136:137], s[40:41], v[40:41] op_sel_hi:[1,0,1]
	v_pk_fma_f32 v[38:39], v[146:147], s[40:41], v[38:39] op_sel_hi:[1,0,1]
	s_nop 0
	v_add_co_u32_e32 v138, vcc, s13, v168
	s_mov_b32 s13, 0x50000
	s_nop 0
	v_addc_co_u32_e32 v139, vcc, 0, v169, vcc
	s_waitcnt vmcnt(7)
	v_lshlrev_b32_e32 v140, 16, v234
	v_and_b32_e32 v141, 0xffff0000, v234
	v_lshlrev_b32_e32 v130, 16, v235
	v_and_b32_e32 v131, 0xffff0000, v235
	s_waitcnt vmcnt(6)
	v_lshlrev_b32_e32 v142, 16, v236
	v_and_b32_e32 v143, 0xffff0000, v236
	v_lshlrev_b32_e32 v132, 16, v237
	v_and_b32_e32 v133, 0xffff0000, v237
	s_waitcnt vmcnt(5)
	v_lshlrev_b32_e32 v144, 16, v238
	v_and_b32_e32 v145, 0xffff0000, v238
	v_lshlrev_b32_e32 v134, 16, v239
	v_and_b32_e32 v135, 0xffff0000, v239
	s_waitcnt vmcnt(4)
	v_lshlrev_b32_e32 v146, 16, v240
	v_and_b32_e32 v147, 0xffff0000, v240
	v_lshlrev_b32_e32 v136, 16, v241
	v_and_b32_e32 v137, 0xffff0000, v241
	v_pk_fma_f32 v[124:125], v[130:131], s[40:41], v[124:125] op_sel_hi:[1,0,1]
	v_pk_fma_f32 v[122:123], v[140:141], s[40:41], v[122:123] op_sel_hi:[1,0,1]
	v_pk_fma_f32 v[96:97], v[132:133], s[40:41], v[96:97] op_sel_hi:[1,0,1]
	v_pk_fma_f32 v[94:95], v[142:143], s[40:41], v[94:95] op_sel_hi:[1,0,1]
	v_pk_fma_f32 v[84:85], v[134:135], s[40:41], v[84:85] op_sel_hi:[1,0,1]
	v_pk_fma_f32 v[82:83], v[144:145], s[40:41], v[82:83] op_sel_hi:[1,0,1]
	v_pk_fma_f32 v[56:57], v[136:137], s[40:41], v[56:57] op_sel_hi:[1,0,1]
	v_pk_fma_f32 v[54:55], v[146:147], s[40:41], v[54:55] op_sel_hi:[1,0,1]
	s_nop 0
	v_add_co_u32_e32 v138, vcc, s13, v168
	s_waitcnt vmcnt(3)
	v_lshlrev_b32_e32 v140, 16, v242
	v_and_b32_e32 v141, 0xffff0000, v242
	v_lshlrev_b32_e32 v130, 16, v243
	v_and_b32_e32 v131, 0xffff0000, v243
	s_waitcnt vmcnt(2)
	v_lshlrev_b32_e32 v142, 16, v244
	v_and_b32_e32 v143, 0xffff0000, v244
	v_lshlrev_b32_e32 v132, 16, v245
	v_and_b32_e32 v133, 0xffff0000, v245
	s_waitcnt vmcnt(1)
	v_lshlrev_b32_e32 v144, 16, v246
	v_and_b32_e32 v145, 0xffff0000, v246
	v_lshlrev_b32_e32 v134, 16, v247
	v_and_b32_e32 v135, 0xffff0000, v247
	s_waitcnt vmcnt(0)
	v_lshlrev_b32_e32 v146, 16, v248
	v_and_b32_e32 v147, 0xffff0000, v248
	v_lshlrev_b32_e32 v136, 16, v249
	v_and_b32_e32 v137, 0xffff0000, v249
	v_pk_fma_f32 v[128:129], v[130:131], s[40:41], v[128:129] op_sel_hi:[1,0,1]
	v_pk_fma_f32 v[126:127], v[140:141], s[40:41], v[126:127] op_sel_hi:[1,0,1]
	v_pk_fma_f32 v[120:121], v[132:133], s[40:41], v[120:121] op_sel_hi:[1,0,1]
	v_pk_fma_f32 v[118:119], v[142:143], s[40:41], v[118:119] op_sel_hi:[1,0,1]
	v_pk_fma_f32 v[104:105], v[134:135], s[40:41], v[104:105] op_sel_hi:[1,0,1]
	v_pk_fma_f32 v[102:103], v[144:145], s[40:41], v[102:103] op_sel_hi:[1,0,1]
	v_pk_fma_f32 v[88:89], v[136:137], s[40:41], v[88:89] op_sel_hi:[1,0,1]
	v_pk_fma_f32 v[86:87], v[146:147], s[40:41], v[86:87] op_sel_hi:[1,0,1]
	v_addc_co_u32_e32 v139, vcc, 0, v169, vcc
	global_load_dwordx2 v[130:131], v[138:139], off
	global_load_dwordx2 v[132:133], v[138:139], off offset:32
	global_load_dwordx2 v[134:135], v[138:139], off offset:256
	global_load_dwordx2 v[136:137], v[138:139], off offset:288
	v_and_b32_e32 v139, 64, v184
	v_xor_b32_e32 v138, 16, v184
	v_add_u32_e32 v139, 64, v139
	v_cmp_lt_i32_e32 vcc, v138, v139
	v_mov_b32_e32 v142, v27
	v_mov_b32_e32 v143, v28
	v_cndmask_b32_e32 v138, v184, v138, vcc
	v_add_co_u32_e32 v140, vcc, s88, v168
	v_mov_b32_e32 v144, v26
	s_nop 0
	v_addc_co_u32_e32 v141, vcc, 0, v169, vcc
	v_mov_b32_e32 v145, v29
	v_pk_add_f32 v[142:143], v[142:143], v[144:145]
	v_mov_b32_e32 v146, v15
	v_mov_b32_e32 v147, v16
	v_add_f32_e32 v142, v142, v143
	v_lshlrev_b32_e32 v138, 2, v138
	s_waitcnt vmcnt(3)
; __device__ __forceinline__ float bf_lo(unsigned w) { return __uint_as_float(w << 16); }
; __device__ __forceinline__ float bf_hi(unsigned w) { return __uint_as_float(w & 0xffff0000u); }
;     __device__ __forceinline__ bool run(const pg8::f32x4 (&v)[2][2][4][2], const pg8::Unit& u, int wr, int wc, int fr, int fq, LAS unsigned char* sl, int wid, int lane) const {
;     ...
;         for (int ai = 0; ai < 2; ++ai)
; #pragma unroll
;             for (int m = 0; m < 4; ++m) {
;                 float s = 0.f;
; #pragma unroll
;                 for (int bj = 0; bj < 2; ++bj)
; #pragma unroll
;                     for (int n = 0; n < 2; ++n) { const pg8::f32x4 x = v[ai][bj][m][n]; s += (x[0] + x[1]) + (x[2] + x[3]); }
;                 s += __shfl_xor(s, 16); s += __shfl_xor(s, 32);
;                 const float mw = s * (1.0f / 64.0f); float q = 0.f;
; #pragma unroll
;                 for (int bj = 0; bj < 2; ++bj)
; #pragma unroll
;                     for (int n = 0; n < 2; ++n) { const pg8::f32x4 d = v[ai][bj][m][n] - mw; q += (d[0] * d[0] + d[1] * d[1]) + (d[2] * d[2] + d[3] * d[3]); }
;                 q += __shfl_xor(q, 16); q += __shfl_xor(q, 32);
;                 if (fq == 0) P[(ai * 128 + wr * 64 + m * 16 + fr) * 4 + wc] = (f32x2v){mw, q};
;     __device__ __forceinline__ void operator()(pg8::f32x4 (&acc)[2][2][4][2], const pg8::Unit& u, int wr, int wc, int fr, int fq) const {
;     ...
;                     for (int n = 0; n < 2; ++n) { const size_t o_ = off0 + (size_t)(ai * 128 + m * 16) * DM + bj * 128 + n * 16; pg8::f32x4 bs;
;                         if (BASE_BF16) { const v2u w = *(const v2u*)((const bf16*)basev + o_); bs = (pg8::f32x4){pg8::bf_lo(w.x), pg8::bf_hi(w.x), pg8::bf_lo(w.y), pg8::bf_hi(w.y)}; }
;                         else bs = *(const pg8::f32x4*)((const float*)basev + o_);
;                         acc[ai][bj][m][n] = bs * ALPHA + acc[ai][bj][m][n]; }
	v_lshlrev_b32_e32 v148, 16, v130
	v_and_b32_e32 v149, 0xffff0000, v130
	v_lshlrev_b32_e32 v130, 16, v131
	v_and_b32_e32 v131, 0xffff0000, v131
	s_waitcnt vmcnt(2)
	v_lshlrev_b32_e32 v170, 16, v132
	v_and_b32_e32 v171, 0xffff0000, v132
	v_lshlrev_b32_e32 v132, 16, v133
	v_and_b32_e32 v133, 0xffff0000, v133
	s_waitcnt vmcnt(1)
	v_lshlrev_b32_e32 v172, 16, v134
	v_and_b32_e32 v173, 0xffff0000, v134
	v_lshlrev_b32_e32 v134, 16, v135
	v_and_b32_e32 v135, 0xffff0000, v135
	s_waitcnt vmcnt(0)
	v_lshlrev_b32_e32 v174, 16, v136
	v_and_b32_e32 v175, 0xffff0000, v136
	v_lshlrev_b32_e32 v136, 16, v137
	v_and_b32_e32 v137, 0xffff0000, v137
	v_pk_fma_f32 v[116:117], v[130:131], s[40:41], v[116:117] op_sel_hi:[1,0,1]
	v_pk_fma_f32 v[114:115], v[148:149], s[40:41], v[114:115] op_sel_hi:[1,0,1]
	v_pk_fma_f32 v[112:113], v[132:133], s[40:41], v[112:113] op_sel_hi:[1,0,1]
	v_pk_fma_f32 v[110:111], v[170:171], s[40:41], v[110:111] op_sel_hi:[1,0,1]
	v_pk_fma_f32 v[108:109], v[134:135], s[40:41], v[108:109] op_sel_hi:[1,0,1]
	v_pk_fma_f32 v[106:107], v[172:173], s[40:41], v[106:107] op_sel_hi:[1,0,1]
	v_pk_fma_f32 v[100:101], v[136:137], s[40:41], v[100:101] op_sel_hi:[1,0,1]
	v_pk_fma_f32 v[98:99], v[174:175], s[40:41], v[98:99] op_sel_hi:[1,0,1]
	v_mov_b32_e32 v136, v14
	global_load_dwordx2 v[130:131], v[140:141], off
	global_load_dwordx2 v[132:133], v[140:141], off offset:32
	global_load_dwordx2 v[134:135], v[140:141], off offset:256
	global_load_dwordx2 v[144:145], v[140:141], off offset:288
	v_mov_b32_e32 v137, v17
	v_pk_add_f32 v[136:137], v[146:147], v[136:137]
	v_add_f32_e32 v149, v6, v7
	v_pk_add_f32 v[136:137], v[136:137], v[136:137] op_sel_hi:[0,1]
	v_add_f32_e32 v171, v8, v9
	v_mov_b32_e32 v148, v2
	v_mov_b32_e32 v170, v3
	v_mov_b32_e32 v172, v5
	v_add_f32_e32 v173, 0, v142
	v_mov_b32_e32 v136, v4
	v_pk_add_f32 v[140:141], v[148:149], v[170:171]
	v_pk_add_f32 v[136:137], v[136:137], v[172:173]
	s_nop 0
	v_pk_add_f32 v[136:137], v[140:141], v[136:137]
	s_nop 0
	v_add_f32_e32 v137, v136, v137
	v_mov_b32_e32 v140, v137
	s_nop 1
	v_permlane16_swap_b32_e32 v140, v137
	v_xor_b32_e32 v136, 32, v184
	v_cmp_lt_i32_e32 vcc, v136, v139
	s_waitcnt lgkmcnt(0)
	v_add_f32_e32 v137, v137, v140
	v_cndmask_b32_e32 v136, v184, v136, vcc
	v_lshlrev_b32_e32 v136, 2, v136
	v_mov_b32_e32 v139, v137
	s_nop 1
	v_permlane32_swap_b32_e32 v139, v137
	s_waitcnt lgkmcnt(0)
	v_add_f32_e32 v137, v137, v139
	v_fmamk_f32 v140, v137, 0xbc800000, v29
	v_fmamk_f32 v142, v137, 0xbc800000, v27
	v_fmamk_f32 v146, v137, 0xbc800000, v17
	v_fmamk_f32 v148, v137, 0xbc800000, v15
	v_fmamk_f32 v139, v137, 0xbc800000, v28
	v_fmamk_f32 v141, v137, 0xbc800000, v26
	v_fmamk_f32 v143, v137, 0xbc800000, v16
	v_fmamk_f32 v147, v137, 0xbc800000, v14
	v_fmamk_f32 v170, v137, 0xbc800000, v9
	v_fmamk_f32 v172, v137, 0xbc800000, v7
	v_mul_f32_e32 v142, v142, v142
	v_mul_f32_e32 v140, v140, v140
	v_mul_f32_e32 v148, v148, v148
	v_mul_f32_e32 v146, v146, v146
	v_fmamk_f32 v149, v137, 0xbc800000, v8
	v_fmamk_f32 v171, v137, 0xbc800000, v6
	v_fmamk_f32 v174, v137, 0xbc800000, v5
	v_fmamk_f32 v176, v137, 0xbc800000, v3
	v_mul_f32_e32 v172, v172, v172
	v_mul_f32_e32 v170, v170, v170
	v_fmac_f32_e32 v142, v141, v141
	v_fmac_f32_e32 v140, v139, v139
	v_fmac_f32_e32 v148, v147, v147
	v_fmac_f32_e32 v146, v143, v143
	v_fmamk_f32 v173, v137, 0xbc800000, v4
	v_fmamk_f32 v175, v137, 0xbc800000, v2
	v_mul_f32_e32 v176, v176, v176
	v_mul_f32_e32 v174, v174, v174
	v_fmac_f32_e32 v172, v171, v171
	v_fmac_f32_e32 v170, v149, v149
	v_add_f32_e32 v139, v142, v140
	v_add_f32_e32 v140, v148, v146
	v_fmac_f32_e32 v176, v175, v175
	v_fmac_f32_e32 v174, v173, v173
	v_add_f32_e32 v141, v172, v170
	v_add_f32_e32 v139, v139, v140
	v_add_f32_e32 v142, v176, v174
	v_add_f32_e32 v139, v141, v139
	v_add_f32_e32 v139, v142, v139
	v_mov_b32_e32 v140, v139
	s_nop 1
	v_permlane16_swap_b32_e32 v140, v139
	s_waitcnt lgkmcnt(0)
	v_add_f32_e32 v139, v139, v140
	v_mov_b32_e32 v140, v139
	s_nop 1
	v_permlane32_swap_b32_e32 v140, v139
	s_waitcnt vmcnt(3)
	v_lshlrev_b32_e32 v142, 16, v130
	v_and_b32_e32 v143, 0xffff0000, v130
	v_lshlrev_b32_e32 v130, 16, v131
	v_and_b32_e32 v131, 0xffff0000, v131
	s_waitcnt vmcnt(2)
	v_lshlrev_b32_e32 v146, 16, v132
	v_and_b32_e32 v147, 0xffff0000, v132
	v_lshlrev_b32_e32 v132, 16, v133
	v_and_b32_e32 v133, 0xffff0000, v133
	s_waitcnt vmcnt(1)
	v_lshlrev_b32_e32 v148, 16, v134
	v_and_b32_e32 v149, 0xffff0000, v134
	v_lshlrev_b32_e32 v134, 16, v135
	v_and_b32_e32 v135, 0xffff0000, v135
	s_waitcnt vmcnt(0)
	v_lshlrev_b32_e32 v170, 16, v144
	v_and_b32_e32 v171, 0xffff0000, v144
	v_lshlrev_b32_e32 v144, 16, v145
	v_and_b32_e32 v145, 0xffff0000, v145
	v_pk_fma_f32 v[72:73], v[130:131], s[40:41], v[72:73] op_sel_hi:[1,0,1]
	v_pk_fma_f32 v[70:71], v[142:143], s[40:41], v[70:71] op_sel_hi:[1,0,1]
	v_pk_fma_f32 v[68:69], v[132:133], s[40:41], v[68:69] op_sel_hi:[1,0,1]
	v_pk_fma_f32 v[66:67], v[146:147], s[40:41], v[66:67] op_sel_hi:[1,0,1]
	v_pk_fma_f32 v[64:65], v[134:135], s[40:41], v[64:65] op_sel_hi:[1,0,1]
	v_pk_fma_f32 v[62:63], v[148:149], s[40:41], v[62:63] op_sel_hi:[1,0,1]
	v_pk_fma_f32 v[60:61], v[144:145], s[40:41], v[60:61] op_sel_hi:[1,0,1]
	v_pk_fma_f32 v[58:59], v[170:171], s[40:41], v[58:59] op_sel_hi:[1,0,1]
	s_nop 0
	s_and_saveexec_b64 s[72:73], s[0:1]
	s_cbranch_execz .LBB0_1603
	v_mul_f32_e32 v130, 0x3c800000, v137
	s_waitcnt lgkmcnt(0)
	v_add_f32_e32 v131, v139, v140
	ds_write_b64 v188, v[130:131]
